# q_up epilogue: per-row rsqrt factors prefetched in one batch (no per-element vmcnt(0) store drain), lane^8 exchange via DPP row_ror:8
# speedup vs baseline: 1.0792x; 1.0028x over previous
.LBB0_888:
	s_and_b64 vcc, exec, s[20:21]
	s_cbranch_vccz .LBB0_799
	v_lshlrev_b32_e32 v134, 2, v140
	v_or_b32_e32 v130, v136, v134
	v_ashrrev_i32_e32 v131, 31, v130
	v_lshlrev_b32_e32 v224, 2, v130
	global_load_dword v192, v224, s[36:37]
	global_load_dword v193, v224, s[36:37] offset:4
	global_load_dword v194, v224, s[36:37] offset:8
	global_load_dword v195, v224, s[36:37] offset:12
	global_load_dword v196, v224, s[36:37] offset:32
	global_load_dword v197, v224, s[36:37] offset:36
	global_load_dword v198, v224, s[36:37] offset:40
	global_load_dword v199, v224, s[36:37] offset:44
	global_load_dword v200, v224, s[36:37] offset:64
	global_load_dword v201, v224, s[36:37] offset:68
	global_load_dword v202, v224, s[36:37] offset:72
	global_load_dword v203, v224, s[36:37] offset:76
	global_load_dword v204, v224, s[36:37] offset:96
	global_load_dword v205, v224, s[36:37] offset:100
	global_load_dword v206, v224, s[36:37] offset:104
	global_load_dword v207, v224, s[36:37] offset:108
	global_load_dword v208, v224, s[36:37] offset:128
	global_load_dword v209, v224, s[36:37] offset:132
	global_load_dword v210, v224, s[36:37] offset:136
	global_load_dword v211, v224, s[36:37] offset:140
	global_load_dword v212, v224, s[36:37] offset:160
	global_load_dword v213, v224, s[36:37] offset:164
	global_load_dword v214, v224, s[36:37] offset:168
	global_load_dword v215, v224, s[36:37] offset:172
	global_load_dword v216, v224, s[36:37] offset:192
	global_load_dword v217, v224, s[36:37] offset:196
	global_load_dword v218, v224, s[36:37] offset:200
	global_load_dword v219, v224, s[36:37] offset:204
	global_load_dword v220, v224, s[36:37] offset:224
	global_load_dword v221, v224, s[36:37] offset:228
	global_load_dword v222, v224, s[36:37] offset:232
	global_load_dword v223, v224, s[36:37] offset:236
	v_lshl_add_u64 v[132:133], v[130:131], 2, s[36:37]
	v_and_b32_e32 v32, 8, v137
	v_and_b32_e32 v133, 64, v169
	v_or_b32_e32 v132, s25, v139
	v_cmp_eq_u32_e32 vcc, 0, v32
	v_xor_b32_e32 v32, 8, v169
	v_add_u32_e32 v133, 64, v133
	v_cmp_lt_i32_e64 s[38:39], v32, v133
	v_lshlrev_b32_e32 v133, 1, v137
	v_ashrrev_i32_e32 v137, 5, v132
	s_mov_b32 s20, 0x55555556
	v_mul_hi_i32 v139, v137, s20
	v_lshrrev_b32_e32 v140, 31, v139
	v_add_u32_e32 v139, v139, v140
	v_lshl_add_u32 v139, v139, 1, v139
	v_cndmask_b32_e64 v32, v169, v32, s[38:39]
	v_sub_u32_e32 v137, v137, v139
	v_lshlrev_b32_e32 v32, 2, v32
	v_cmp_eq_u32_e64 s[38:39], 2, v137
	s_andn2_b32 s24, s24, 63
	s_cmp_eq_u32 s24, 64
	s_cselect_b64 s[0:1], -1, 0
	v_bfe_u32 v135, v136, 6, 4
	v_and_b32_e32 v133, 14, v133
	s_and_b64 s[20:21], s[0:1], s[38:39]
	v_cmp_gt_u32_e64 s[38:39], 16, v138
	s_waitcnt vmcnt(0)
	v_mov_b32_e32 v131, v192
	v_mul_f32_e32 v137, v50, v131
	s_nop 1
	v_mov_b32_dpp v139, v137 row_ror:8 row_mask:0xf bank_mask:0xf
	v_lshlrev_b32_e32 v50, 2, v133
	v_cndmask_b32_e64 v133, v134, v135, s[38:39]
	s_and_saveexec_b64 s[28:29], s[20:21]
	s_cbranch_execz .LBB0_891
	v_lshl_or_b32 v140, v133, 6, v50
	global_load_dwordx2 v[140:141], v140, s[76:77]
	s_waitcnt vmcnt(0) lgkmcnt(0)
	v_mul_f32_e32 v139, v141, v139
	v_cndmask_b32_e64 v139, v139, -v139, vcc
	v_fmac_f32_e32 v139, v137, v140
	v_mov_b32_e32 v137, v139
.LBB0_891:
	s_or_b64 exec, exec, s[28:29]
	s_movk_i32 s24, 0x300
	v_or_b32_e32 v142, 1, v134
	v_mul_lo_u32 v130, v130, s24
	v_or_b32_e32 v140, v136, v142
	v_or_b32_e32 v130, v130, v138
	v_ashrrev_i32_e32 v141, 31, v140
	v_add_lshl_u32 v138, v130, v132, 1
	v_cvt_pk_bf16_f32 v137, v137, s0
	v_lshl_add_u64 v[140:141], v[140:141], 2, s[36:37]
	global_store_short v138, v137, s[66:67]
	v_mov_b32_e32 v137, v193
	s_waitcnt lgkmcnt(0)
	v_mul_f32_e32 v139, v51, v137
	s_nop 1
	v_mov_b32_dpp v140, v139 row_ror:8 row_mask:0xf bank_mask:0xf
	v_cndmask_b32_e64 v51, v142, v135, s[38:39]
	s_and_saveexec_b64 s[28:29], s[20:21]
	s_cbranch_execz .LBB0_893
	v_lshl_or_b32 v141, v51, 6, v50
	global_load_dwordx2 v[142:143], v141, s[76:77]
	s_waitcnt vmcnt(0) lgkmcnt(0)
	v_mul_f32_e32 v140, v143, v140
	v_cndmask_b32_e64 v140, v140, -v140, vcc
	v_fmac_f32_e32 v140, v139, v142
	v_mov_b32_e32 v139, v140
.LBB0_893:
	s_or_b64 exec, exec, s[28:29]
	s_waitcnt lgkmcnt(0)
	v_add_u32_e32 v140, 0x600, v138
	v_cvt_pk_bf16_f32 v139, v139, s0
	v_or_b32_e32 v142, 2, v134
	global_store_short v140, v139, s[66:67]
	v_or_b32_e32 v140, v136, v142
	v_ashrrev_i32_e32 v141, 31, v140
	v_lshl_add_u64 v[140:141], v[140:141], 2, s[36:37]
	v_mov_b32_e32 v139, v194
	s_nop 0
	v_mul_f32_e32 v140, v52, v139
	s_nop 1
	v_mov_b32_dpp v141, v140 row_ror:8 row_mask:0xf bank_mask:0xf
	v_cndmask_b32_e64 v52, v142, v135, s[38:39]
	s_and_saveexec_b64 s[28:29], s[20:21]
	s_cbranch_execz .LBB0_895
	v_lshl_or_b32 v142, v52, 6, v50
	global_load_dwordx2 v[142:143], v142, s[76:77]
	s_waitcnt vmcnt(0) lgkmcnt(0)
	v_mul_f32_e32 v141, v143, v141
	v_cndmask_b32_e64 v141, v141, -v141, vcc
	v_fmac_f32_e32 v141, v140, v142
	v_mov_b32_e32 v140, v141
.LBB0_895:
	s_or_b64 exec, exec, s[28:29]
	s_waitcnt lgkmcnt(0)
	v_add_u32_e32 v141, 0xc00, v138
	v_cvt_pk_bf16_f32 v140, v140, s0
	v_or_b32_e32 v143, 3, v134
	global_store_short v141, v140, s[66:67]
	v_or_b32_e32 v140, v136, v143
	v_ashrrev_i32_e32 v141, 31, v140
	v_lshl_add_u64 v[140:141], v[140:141], 2, s[36:37]
	v_mov_b32_e32 v140, v195
	s_nop 0
	v_mul_f32_e32 v141, v53, v140
	s_nop 1
	v_mov_b32_dpp v142, v141 row_ror:8 row_mask:0xf bank_mask:0xf
	v_cndmask_b32_e64 v53, v143, v135, s[38:39]
	s_and_saveexec_b64 s[28:29], s[20:21]
	s_cbranch_execz .LBB0_897
	v_lshl_or_b32 v143, v53, 6, v50
	global_load_dwordx2 v[144:145], v143, s[76:77]
	s_waitcnt vmcnt(0) lgkmcnt(0)
	v_mul_f32_e32 v142, v145, v142
	v_cndmask_b32_e64 v142, v142, -v142, vcc
	v_fmac_f32_e32 v142, v141, v144
	v_mov_b32_e32 v141, v142
.LBB0_897:
	s_or_b64 exec, exec, s[28:29]
	s_waitcnt lgkmcnt(0)
	v_add_u32_e32 v142, 0x1200, v138
	v_cvt_pk_bf16_f32 v141, v141, s0
	v_or_b32_e32 v144, 8, v134
	global_store_short v142, v141, s[66:67]
	v_or_b32_e32 v142, v136, v144
	v_ashrrev_i32_e32 v143, 31, v142
	v_lshl_add_u64 v[142:143], v[142:143], 2, s[36:37]
	v_mov_b32_e32 v141, v196
	s_nop 0
	v_mul_f32_e32 v142, v54, v141
	s_nop 1
	v_mov_b32_dpp v143, v142 row_ror:8 row_mask:0xf bank_mask:0xf
	v_cndmask_b32_e64 v54, v144, v135, s[38:39]
	s_and_saveexec_b64 s[28:29], s[20:21]
	s_cbranch_execz .LBB0_899
	v_lshl_or_b32 v144, v54, 6, v50
	global_load_dwordx2 v[144:145], v144, s[76:77]
	s_waitcnt vmcnt(0) lgkmcnt(0)
	v_mul_f32_e32 v143, v145, v143
	v_cndmask_b32_e64 v143, v143, -v143, vcc
	v_fmac_f32_e32 v143, v142, v144
	v_mov_b32_e32 v142, v143
.LBB0_899:
	s_or_b64 exec, exec, s[28:29]
	s_waitcnt lgkmcnt(0)
	v_add_u32_e32 v143, 0x3000, v138
	v_cvt_pk_bf16_f32 v142, v142, s0
	v_or_b32_e32 v145, 9, v134
	global_store_short v143, v142, s[66:67]
	v_or_b32_e32 v142, v136, v145
	v_ashrrev_i32_e32 v143, 31, v142
	v_lshl_add_u64 v[142:143], v[142:143], 2, s[36:37]
	v_mov_b32_e32 v142, v197
	s_nop 0
	v_mul_f32_e32 v143, v55, v142
	s_nop 1
	v_mov_b32_dpp v144, v143 row_ror:8 row_mask:0xf bank_mask:0xf
	v_cndmask_b32_e64 v55, v145, v135, s[38:39]
	s_and_saveexec_b64 s[28:29], s[20:21]
	s_cbranch_execz .LBB0_901
	v_lshl_or_b32 v145, v55, 6, v50
	global_load_dwordx2 v[146:147], v145, s[76:77]
	s_waitcnt vmcnt(0) lgkmcnt(0)
	v_mul_f32_e32 v144, v147, v144
	v_cndmask_b32_e64 v144, v144, -v144, vcc
	v_fmac_f32_e32 v144, v143, v146
	v_mov_b32_e32 v143, v144
.LBB0_901:
	s_or_b64 exec, exec, s[28:29]
	s_waitcnt lgkmcnt(0)
	v_add_u32_e32 v144, 0x3600, v138
	v_cvt_pk_bf16_f32 v143, v143, s0
	v_or_b32_e32 v146, 10, v134
	global_store_short v144, v143, s[66:67]
	v_or_b32_e32 v144, v136, v146
	v_ashrrev_i32_e32 v145, 31, v144
	v_lshl_add_u64 v[144:145], v[144:145], 2, s[36:37]
	v_mov_b32_e32 v143, v198
	s_nop 0
	v_mul_f32_e32 v144, v56, v143
	s_nop 1
	v_mov_b32_dpp v145, v144 row_ror:8 row_mask:0xf bank_mask:0xf
	v_cndmask_b32_e64 v56, v146, v135, s[38:39]
	s_and_saveexec_b64 s[28:29], s[20:21]
	s_cbranch_execz .LBB0_903
	v_lshl_or_b32 v146, v56, 6, v50
	global_load_dwordx2 v[146:147], v146, s[76:77]
	s_waitcnt vmcnt(0) lgkmcnt(0)
	v_mul_f32_e32 v145, v147, v145
	v_cndmask_b32_e64 v145, v145, -v145, vcc
	v_fmac_f32_e32 v145, v144, v146
	v_mov_b32_e32 v144, v145
.LBB0_903:
	s_or_b64 exec, exec, s[28:29]
	s_waitcnt lgkmcnt(0)
	v_add_u32_e32 v145, 0x3c00, v138
	v_cvt_pk_bf16_f32 v144, v144, s0
	v_or_b32_e32 v147, 11, v134
	global_store_short v145, v144, s[66:67]
	v_or_b32_e32 v144, v136, v147
	v_ashrrev_i32_e32 v145, 31, v144
	v_lshl_add_u64 v[144:145], v[144:145], 2, s[36:37]
	v_mov_b32_e32 v144, v199
	s_nop 0
	v_mul_f32_e32 v145, v57, v144
	s_nop 1
	v_mov_b32_dpp v146, v145 row_ror:8 row_mask:0xf bank_mask:0xf
	v_cndmask_b32_e64 v57, v147, v135, s[38:39]
	s_and_saveexec_b64 s[28:29], s[20:21]
	s_cbranch_execz .LBB0_905
	v_lshl_or_b32 v147, v57, 6, v50
	global_load_dwordx2 v[148:149], v147, s[76:77]
	s_waitcnt vmcnt(0) lgkmcnt(0)
	v_mul_f32_e32 v146, v149, v146
	v_cndmask_b32_e64 v146, v146, -v146, vcc
	v_fmac_f32_e32 v146, v145, v148
	v_mov_b32_e32 v145, v146
.LBB0_905:
	s_or_b64 exec, exec, s[28:29]
	s_waitcnt lgkmcnt(0)
	v_add_u32_e32 v146, 0x4200, v138
	v_cvt_pk_bf16_f32 v145, v145, s0
	v_or_b32_e32 v148, 16, v134
	global_store_short v146, v145, s[66:67]
	v_or_b32_e32 v146, v136, v148
	v_ashrrev_i32_e32 v147, 31, v146
	v_lshl_add_u64 v[146:147], v[146:147], 2, s[36:37]
	v_mov_b32_e32 v145, v200
	s_nop 0
	v_mul_f32_e32 v146, v58, v145
	s_nop 1
	v_mov_b32_dpp v147, v146 row_ror:8 row_mask:0xf bank_mask:0xf
	v_cndmask_b32_e64 v58, v148, v135, s[38:39]
	s_and_saveexec_b64 s[28:29], s[20:21]
	s_cbranch_execz .LBB0_907
	v_lshl_or_b32 v148, v58, 6, v50
	global_load_dwordx2 v[148:149], v148, s[76:77]
	s_waitcnt vmcnt(0) lgkmcnt(0)
	v_mul_f32_e32 v147, v149, v147
	v_cndmask_b32_e64 v147, v147, -v147, vcc
	v_fmac_f32_e32 v147, v146, v148
	v_mov_b32_e32 v146, v147
.LBB0_907:
	s_or_b64 exec, exec, s[28:29]
	s_waitcnt lgkmcnt(0)
	v_add_u32_e32 v147, 0x6000, v138
	v_cvt_pk_bf16_f32 v146, v146, s0
	v_or_b32_e32 v149, 17, v134
	global_store_short v147, v146, s[66:67]
	v_or_b32_e32 v146, v136, v149
	v_ashrrev_i32_e32 v147, 31, v146
	v_lshl_add_u64 v[146:147], v[146:147], 2, s[36:37]
	v_mov_b32_e32 v146, v201
	s_nop 0
	v_mul_f32_e32 v147, v59, v146
	s_nop 1
	v_mov_b32_dpp v148, v147 row_ror:8 row_mask:0xf bank_mask:0xf
	v_cndmask_b32_e64 v59, v149, v135, s[38:39]
	s_and_saveexec_b64 s[28:29], s[20:21]
	s_cbranch_execz .LBB0_909
	v_lshl_or_b32 v149, v59, 6, v50
	global_load_dwordx2 v[150:151], v149, s[76:77]
	s_waitcnt vmcnt(0) lgkmcnt(0)
	v_mul_f32_e32 v148, v151, v148
	v_cndmask_b32_e64 v148, v148, -v148, vcc
	v_fmac_f32_e32 v148, v147, v150
	v_mov_b32_e32 v147, v148
.LBB0_909:
	s_or_b64 exec, exec, s[28:29]
	s_waitcnt lgkmcnt(0)
	v_add_u32_e32 v148, 0x6600, v138
	v_cvt_pk_bf16_f32 v147, v147, s0
	v_or_b32_e32 v150, 18, v134
	global_store_short v148, v147, s[66:67]
	v_or_b32_e32 v148, v136, v150
	v_ashrrev_i32_e32 v149, 31, v148
	v_lshl_add_u64 v[148:149], v[148:149], 2, s[36:37]
	v_mov_b32_e32 v147, v202
	s_nop 0
	v_mul_f32_e32 v148, v60, v147
	s_nop 1
	v_mov_b32_dpp v149, v148 row_ror:8 row_mask:0xf bank_mask:0xf
	v_cndmask_b32_e64 v60, v150, v135, s[38:39]
	s_and_saveexec_b64 s[28:29], s[20:21]
	s_cbranch_execz .LBB0_911
	v_lshl_or_b32 v150, v60, 6, v50
	global_load_dwordx2 v[150:151], v150, s[76:77]
	s_waitcnt vmcnt(0) lgkmcnt(0)
	v_mul_f32_e32 v149, v151, v149
	v_cndmask_b32_e64 v149, v149, -v149, vcc
	v_fmac_f32_e32 v149, v148, v150
	v_mov_b32_e32 v148, v149
.LBB0_911:
	s_or_b64 exec, exec, s[28:29]
	s_waitcnt lgkmcnt(0)
	v_add_u32_e32 v149, 0x6c00, v138
	v_cvt_pk_bf16_f32 v148, v148, s0
	v_or_b32_e32 v151, 19, v134
	global_store_short v149, v148, s[66:67]
	v_or_b32_e32 v148, v136, v151
	v_ashrrev_i32_e32 v149, 31, v148
	v_lshl_add_u64 v[148:149], v[148:149], 2, s[36:37]
	v_mov_b32_e32 v148, v203
	s_nop 0
	v_mul_f32_e32 v149, v61, v148
	s_nop 1
	v_mov_b32_dpp v150, v149 row_ror:8 row_mask:0xf bank_mask:0xf
	v_cndmask_b32_e64 v61, v151, v135, s[38:39]
	s_and_saveexec_b64 s[28:29], s[20:21]
	s_cbranch_execz .LBB0_913
	v_lshl_or_b32 v151, v61, 6, v50
	global_load_dwordx2 v[152:153], v151, s[76:77]
	s_waitcnt vmcnt(0) lgkmcnt(0)
	v_mul_f32_e32 v150, v153, v150
	v_cndmask_b32_e64 v150, v150, -v150, vcc
	v_fmac_f32_e32 v150, v149, v152
	v_mov_b32_e32 v149, v150
.LBB0_913:
	s_or_b64 exec, exec, s[28:29]
	s_waitcnt lgkmcnt(0)
	v_add_u32_e32 v150, 0x7200, v138
	v_cvt_pk_bf16_f32 v149, v149, s0
	v_or_b32_e32 v152, 24, v134
	global_store_short v150, v149, s[66:67]
	v_or_b32_e32 v150, v136, v152
	v_ashrrev_i32_e32 v151, 31, v150
	v_lshl_add_u64 v[150:151], v[150:151], 2, s[36:37]
	v_mov_b32_e32 v149, v204
	s_nop 0
	v_mul_f32_e32 v150, v62, v149
	s_nop 1
	v_mov_b32_dpp v151, v150 row_ror:8 row_mask:0xf bank_mask:0xf
	v_cndmask_b32_e64 v62, v152, v135, s[38:39]
	s_and_saveexec_b64 s[28:29], s[20:21]
	s_cbranch_execz .LBB0_915
	v_lshl_or_b32 v152, v62, 6, v50
	global_load_dwordx2 v[152:153], v152, s[76:77]
	s_waitcnt vmcnt(0) lgkmcnt(0)
	v_mul_f32_e32 v151, v153, v151
	v_cndmask_b32_e64 v151, v151, -v151, vcc
	v_fmac_f32_e32 v151, v150, v152
	v_mov_b32_e32 v150, v151
.LBB0_915:
	s_or_b64 exec, exec, s[28:29]
	s_waitcnt lgkmcnt(0)
	v_add_u32_e32 v151, 0x9000, v138
	v_cvt_pk_bf16_f32 v150, v150, s0
	v_or_b32_e32 v153, 25, v134
	global_store_short v151, v150, s[66:67]
	v_or_b32_e32 v150, v136, v153
	v_ashrrev_i32_e32 v151, 31, v150
	v_lshl_add_u64 v[150:151], v[150:151], 2, s[36:37]
	v_mov_b32_e32 v150, v205
	s_nop 0
	v_mul_f32_e32 v151, v63, v150
	s_nop 1
	v_mov_b32_dpp v152, v151 row_ror:8 row_mask:0xf bank_mask:0xf
	v_cndmask_b32_e64 v63, v153, v135, s[38:39]
	s_and_saveexec_b64 s[28:29], s[20:21]
	s_cbranch_execz .LBB0_917
	v_lshl_or_b32 v153, v63, 6, v50
	global_load_dwordx2 v[154:155], v153, s[76:77]
	s_waitcnt vmcnt(0) lgkmcnt(0)
	v_mul_f32_e32 v152, v155, v152
	v_cndmask_b32_e64 v152, v152, -v152, vcc
	v_fmac_f32_e32 v152, v151, v154
	v_mov_b32_e32 v151, v152
.LBB0_917:
	s_or_b64 exec, exec, s[28:29]
	s_waitcnt lgkmcnt(0)
	v_add_u32_e32 v152, 0x9600, v138
	v_cvt_pk_bf16_f32 v151, v151, s0
	v_or_b32_e32 v154, 26, v134
	global_store_short v152, v151, s[66:67]
	v_or_b32_e32 v152, v136, v154
	v_ashrrev_i32_e32 v153, 31, v152
	v_lshl_add_u64 v[152:153], v[152:153], 2, s[36:37]
	v_mov_b32_e32 v151, v206
	s_nop 0
	v_mul_f32_e32 v152, v64, v151
	s_nop 1
	v_mov_b32_dpp v153, v152 row_ror:8 row_mask:0xf bank_mask:0xf
	v_cndmask_b32_e64 v64, v154, v135, s[38:39]
	s_and_saveexec_b64 s[28:29], s[20:21]
	s_cbranch_execz .LBB0_919
	v_lshl_or_b32 v154, v64, 6, v50
	global_load_dwordx2 v[154:155], v154, s[76:77]
	s_waitcnt vmcnt(0) lgkmcnt(0)
	v_mul_f32_e32 v153, v155, v153
	v_cndmask_b32_e64 v153, v153, -v153, vcc
	v_fmac_f32_e32 v153, v152, v154
	v_mov_b32_e32 v152, v153
.LBB0_919:
	s_or_b64 exec, exec, s[28:29]
	s_waitcnt lgkmcnt(0)
	v_add_u32_e32 v153, 0x9c00, v138
	v_cvt_pk_bf16_f32 v152, v152, s0
	v_or_b32_e32 v155, 27, v134
	global_store_short v153, v152, s[66:67]
	v_or_b32_e32 v152, v136, v155
	v_ashrrev_i32_e32 v153, 31, v152
	v_lshl_add_u64 v[152:153], v[152:153], 2, s[36:37]
	v_mov_b32_e32 v152, v207
	s_nop 0
	v_mul_f32_e32 v153, v65, v152
	s_nop 1
	v_mov_b32_dpp v154, v153 row_ror:8 row_mask:0xf bank_mask:0xf
	v_cndmask_b32_e64 v65, v155, v135, s[38:39]
	s_and_saveexec_b64 s[28:29], s[20:21]
	s_cbranch_execz .LBB0_921
	v_lshl_or_b32 v155, v65, 6, v50
	global_load_dwordx2 v[156:157], v155, s[76:77]
	s_waitcnt vmcnt(0) lgkmcnt(0)
	v_mul_f32_e32 v154, v157, v154
	v_cndmask_b32_e64 v154, v154, -v154, vcc
	v_fmac_f32_e32 v154, v153, v156
	v_mov_b32_e32 v153, v154
.LBB0_921:
	s_or_b64 exec, exec, s[28:29]
	s_waitcnt lgkmcnt(0)
	v_add_u32_e32 v154, 0xa200, v138
	v_cvt_pk_bf16_f32 v153, v153, s0
	v_or_b32_e32 v156, 32, v134
	global_store_short v154, v153, s[66:67]
	v_or_b32_e32 v154, v136, v156
	v_ashrrev_i32_e32 v155, 31, v154
	v_lshl_add_u64 v[154:155], v[154:155], 2, s[36:37]
	v_mov_b32_e32 v153, v208
	s_nop 0
	v_mul_f32_e32 v154, v34, v153
	s_nop 1
	v_mov_b32_dpp v155, v154 row_ror:8 row_mask:0xf bank_mask:0xf
	v_cndmask_b32_e64 v34, v156, v135, s[38:39]
	s_and_saveexec_b64 s[28:29], s[20:21]
	s_cbranch_execz .LBB0_923
	v_lshl_or_b32 v156, v34, 6, v50
	global_load_dwordx2 v[156:157], v156, s[76:77]
	s_waitcnt vmcnt(0) lgkmcnt(0)
	v_mul_f32_e32 v155, v157, v155
	v_cndmask_b32_e64 v155, v155, -v155, vcc
	v_fmac_f32_e32 v155, v154, v156
	v_mov_b32_e32 v154, v155
.LBB0_923:
	s_or_b64 exec, exec, s[28:29]
	s_waitcnt lgkmcnt(0)
	v_add_u32_e32 v155, 0xc000, v138
	v_cvt_pk_bf16_f32 v154, v154, s0
	v_or_b32_e32 v157, 33, v134
	global_store_short v155, v154, s[66:67]
	v_or_b32_e32 v154, v136, v157
	v_ashrrev_i32_e32 v155, 31, v154
	v_lshl_add_u64 v[154:155], v[154:155], 2, s[36:37]
	v_mov_b32_e32 v154, v209
	s_nop 0
	v_mul_f32_e32 v155, v35, v154
	s_nop 1
	v_mov_b32_dpp v156, v155 row_ror:8 row_mask:0xf bank_mask:0xf
	v_cndmask_b32_e64 v35, v157, v135, s[38:39]
	s_and_saveexec_b64 s[28:29], s[20:21]
	s_cbranch_execz .LBB0_925
	v_lshl_or_b32 v157, v35, 6, v50
	global_load_dwordx2 v[160:161], v157, s[76:77]
	s_waitcnt vmcnt(0) lgkmcnt(0)
	v_mul_f32_e32 v156, v161, v156
	v_cndmask_b32_e64 v156, v156, -v156, vcc
	v_fmac_f32_e32 v156, v155, v160
	v_mov_b32_e32 v155, v156
.LBB0_925:
	s_or_b64 exec, exec, s[28:29]
	s_waitcnt lgkmcnt(0)
	v_add_u32_e32 v156, 0xc600, v138
	v_cvt_pk_bf16_f32 v155, v155, s0
	v_or_b32_e32 v160, 34, v134
	global_store_short v156, v155, s[66:67]
	v_or_b32_e32 v156, v136, v160
	v_ashrrev_i32_e32 v157, 31, v156
	v_lshl_add_u64 v[156:157], v[156:157], 2, s[36:37]
	v_mov_b32_e32 v155, v210
	s_nop 0
	v_mul_f32_e32 v156, v36, v155
	s_nop 1
	v_mov_b32_dpp v157, v156 row_ror:8 row_mask:0xf bank_mask:0xf
	v_cndmask_b32_e64 v36, v160, v135, s[38:39]
	s_and_saveexec_b64 s[28:29], s[20:21]
	s_cbranch_execz .LBB0_927
	v_lshl_or_b32 v160, v36, 6, v50
	global_load_dwordx2 v[160:161], v160, s[76:77]
	s_waitcnt vmcnt(0) lgkmcnt(0)
	v_mul_f32_e32 v157, v161, v157
	v_cndmask_b32_e64 v157, v157, -v157, vcc
	v_fmac_f32_e32 v157, v156, v160
	v_mov_b32_e32 v156, v157
.LBB0_927:
	s_or_b64 exec, exec, s[28:29]
	s_waitcnt lgkmcnt(0)
	v_add_u32_e32 v157, 0xcc00, v138
	v_cvt_pk_bf16_f32 v156, v156, s0
	v_or_b32_e32 v161, 35, v134
	global_store_short v157, v156, s[66:67]
	v_or_b32_e32 v156, v136, v161
	v_ashrrev_i32_e32 v157, 31, v156
	v_lshl_add_u64 v[156:157], v[156:157], 2, s[36:37]
	v_mov_b32_e32 v156, v211
	s_nop 0
	v_mul_f32_e32 v157, v37, v156
	s_nop 1
	v_mov_b32_dpp v160, v157 row_ror:8 row_mask:0xf bank_mask:0xf
	v_cndmask_b32_e64 v37, v161, v135, s[38:39]
	s_and_saveexec_b64 s[28:29], s[20:21]
	s_cbranch_execz .LBB0_929
	v_lshl_or_b32 v161, v37, 6, v50
	global_load_dwordx2 v[180:181], v161, s[76:77]
	s_waitcnt vmcnt(0) lgkmcnt(0)
	v_mul_f32_e32 v160, v181, v160
	v_cndmask_b32_e64 v160, v160, -v160, vcc
	v_fmac_f32_e32 v160, v157, v180
	v_mov_b32_e32 v157, v160
.LBB0_929:
	s_or_b64 exec, exec, s[28:29]
	s_waitcnt lgkmcnt(0)
	v_add_u32_e32 v160, 0xd200, v138
	v_cvt_pk_bf16_f32 v157, v157, s0
	v_or_b32_e32 v180, 40, v134
	global_store_short v160, v157, s[66:67]
	v_or_b32_e32 v160, v136, v180
	v_ashrrev_i32_e32 v161, 31, v160
	v_lshl_add_u64 v[160:161], v[160:161], 2, s[36:37]
	v_mov_b32_e32 v157, v212
	s_nop 0
	v_mul_f32_e32 v160, v38, v157
	s_nop 1
	v_mov_b32_dpp v161, v160 row_ror:8 row_mask:0xf bank_mask:0xf
	v_cndmask_b32_e64 v38, v180, v135, s[38:39]
	s_and_saveexec_b64 s[28:29], s[20:21]
	s_cbranch_execz .LBB0_931
	v_lshl_or_b32 v180, v38, 6, v50
	global_load_dwordx2 v[180:181], v180, s[76:77]
	s_waitcnt vmcnt(0) lgkmcnt(0)
	v_mul_f32_e32 v161, v181, v161
	v_cndmask_b32_e64 v161, v161, -v161, vcc
	v_fmac_f32_e32 v161, v160, v180
	v_mov_b32_e32 v160, v161
.LBB0_931:
	s_or_b64 exec, exec, s[28:29]
	s_waitcnt lgkmcnt(0)
	v_add_u32_e32 v161, 0xf000, v138
	v_cvt_pk_bf16_f32 v160, v160, s0
	v_or_b32_e32 v181, 41, v134
	global_store_short v161, v160, s[66:67]
	v_or_b32_e32 v160, v136, v181
	v_ashrrev_i32_e32 v161, 31, v160
	v_lshl_add_u64 v[160:161], v[160:161], 2, s[36:37]
	v_mov_b32_e32 v160, v213
	s_nop 0
	v_mul_f32_e32 v161, v39, v160
	s_nop 1
	v_mov_b32_dpp v180, v161 row_ror:8 row_mask:0xf bank_mask:0xf
	v_cndmask_b32_e64 v39, v181, v135, s[38:39]
	s_and_saveexec_b64 s[28:29], s[20:21]
	s_cbranch_execz .LBB0_933
	v_lshl_or_b32 v181, v39, 6, v50
	global_load_dwordx2 v[182:183], v181, s[76:77]
	s_waitcnt vmcnt(0) lgkmcnt(0)
	v_mul_f32_e32 v180, v183, v180
	v_cndmask_b32_e64 v180, v180, -v180, vcc
	v_fmac_f32_e32 v180, v161, v182
	v_mov_b32_e32 v161, v180
.LBB0_933:
	s_or_b64 exec, exec, s[28:29]
	s_waitcnt lgkmcnt(0)
	v_add_u32_e32 v180, 0xf600, v138
	v_cvt_pk_bf16_f32 v161, v161, s0
	v_or_b32_e32 v182, 42, v134
	global_store_short v180, v161, s[66:67]
	v_or_b32_e32 v180, v136, v182
	v_ashrrev_i32_e32 v181, 31, v180
	v_lshl_add_u64 v[180:181], v[180:181], 2, s[36:37]
	v_mov_b32_e32 v161, v214
	s_nop 0
	v_mul_f32_e32 v180, v40, v161
	s_nop 1
	v_mov_b32_dpp v181, v180 row_ror:8 row_mask:0xf bank_mask:0xf
	v_cndmask_b32_e64 v40, v182, v135, s[38:39]
	s_and_saveexec_b64 s[28:29], s[20:21]
	s_cbranch_execz .LBB0_935
	v_lshl_or_b32 v182, v40, 6, v50
	global_load_dwordx2 v[182:183], v182, s[76:77]
	s_waitcnt vmcnt(0) lgkmcnt(0)
	v_mul_f32_e32 v181, v183, v181
	v_cndmask_b32_e64 v181, v181, -v181, vcc
	v_fmac_f32_e32 v181, v180, v182
	v_mov_b32_e32 v180, v181
.LBB0_935:
	s_or_b64 exec, exec, s[28:29]
	s_waitcnt lgkmcnt(0)
	v_add_u32_e32 v181, 0xfc00, v138
	v_cvt_pk_bf16_f32 v180, v180, s0
	v_or_b32_e32 v183, 43, v134
	global_store_short v181, v180, s[66:67]
	v_or_b32_e32 v180, v136, v183
	v_ashrrev_i32_e32 v181, 31, v180
	v_lshl_add_u64 v[180:181], v[180:181], 2, s[36:37]
	v_mov_b32_e32 v180, v215
	s_nop 0
	v_mul_f32_e32 v181, v41, v180
	s_nop 1
	v_mov_b32_dpp v182, v181 row_ror:8 row_mask:0xf bank_mask:0xf
	v_cndmask_b32_e64 v41, v183, v135, s[38:39]
	s_and_saveexec_b64 s[28:29], s[20:21]
	s_cbranch_execz .LBB0_937
	v_lshl_or_b32 v183, v41, 6, v50
	global_load_dwordx2 v[184:185], v183, s[76:77]
	s_waitcnt vmcnt(0) lgkmcnt(0)
	v_mul_f32_e32 v182, v185, v182
	v_cndmask_b32_e64 v182, v182, -v182, vcc
	v_fmac_f32_e32 v182, v181, v184
	v_mov_b32_e32 v181, v182
.LBB0_937:
	s_or_b64 exec, exec, s[28:29]
	s_waitcnt lgkmcnt(0)
	v_add_u32_e32 v182, 0x10200, v138
	v_cvt_pk_bf16_f32 v181, v181, s0
	v_or_b32_e32 v184, 48, v134
	global_store_short v182, v181, s[66:67]
	v_or_b32_e32 v182, v136, v184
	v_ashrrev_i32_e32 v183, 31, v182
	v_lshl_add_u64 v[182:183], v[182:183], 2, s[36:37]
	v_mov_b32_e32 v181, v216
	s_nop 0
	v_mul_f32_e32 v182, v42, v181
	s_nop 1
	v_mov_b32_dpp v183, v182 row_ror:8 row_mask:0xf bank_mask:0xf
	v_cndmask_b32_e64 v42, v184, v135, s[38:39]
	s_and_saveexec_b64 s[28:29], s[20:21]
	s_cbranch_execz .LBB0_939
	v_lshl_or_b32 v184, v42, 6, v50
	global_load_dwordx2 v[184:185], v184, s[76:77]
	s_waitcnt vmcnt(0) lgkmcnt(0)
	v_mul_f32_e32 v183, v185, v183
	v_cndmask_b32_e64 v183, v183, -v183, vcc
	v_fmac_f32_e32 v183, v182, v184
	v_mov_b32_e32 v182, v183
.LBB0_939:
	s_or_b64 exec, exec, s[28:29]
	s_waitcnt lgkmcnt(0)
	v_add_u32_e32 v183, 0x12000, v138
	v_cvt_pk_bf16_f32 v182, v182, s0
	v_or_b32_e32 v185, 49, v134
	global_store_short v183, v182, s[66:67]
	v_or_b32_e32 v182, v136, v185
	v_ashrrev_i32_e32 v183, 31, v182
	v_lshl_add_u64 v[182:183], v[182:183], 2, s[36:37]
	v_mov_b32_e32 v182, v217
	s_nop 0
	v_mul_f32_e32 v183, v43, v182
	s_nop 1
	v_mov_b32_dpp v184, v183 row_ror:8 row_mask:0xf bank_mask:0xf
	v_cndmask_b32_e64 v43, v185, v135, s[38:39]
	s_and_saveexec_b64 s[28:29], s[20:21]
	s_cbranch_execz .LBB0_941
	v_lshl_or_b32 v185, v43, 6, v50
	global_load_dwordx2 v[186:187], v185, s[76:77]
	s_waitcnt vmcnt(0) lgkmcnt(0)
	v_mul_f32_e32 v184, v187, v184
	v_cndmask_b32_e64 v184, v184, -v184, vcc
	v_fmac_f32_e32 v184, v183, v186
	v_mov_b32_e32 v183, v184
.LBB0_941:
	s_or_b64 exec, exec, s[28:29]
	s_waitcnt lgkmcnt(0)
	v_add_u32_e32 v184, 0x12600, v138
	v_cvt_pk_bf16_f32 v183, v183, s0
	v_or_b32_e32 v186, 50, v134
	global_store_short v184, v183, s[66:67]
	v_or_b32_e32 v184, v136, v186
	v_ashrrev_i32_e32 v185, 31, v184
	v_lshl_add_u64 v[184:185], v[184:185], 2, s[36:37]
	v_mov_b32_e32 v183, v218
	s_nop 0
	v_mul_f32_e32 v184, v44, v183
	s_nop 1
	v_mov_b32_dpp v185, v184 row_ror:8 row_mask:0xf bank_mask:0xf
	v_cndmask_b32_e64 v44, v186, v135, s[38:39]
	s_and_saveexec_b64 s[28:29], s[20:21]
	s_cbranch_execz .LBB0_943
	v_lshl_or_b32 v186, v44, 6, v50
	global_load_dwordx2 v[186:187], v186, s[76:77]
	s_waitcnt vmcnt(0) lgkmcnt(0)
	v_mul_f32_e32 v185, v187, v185
	v_cndmask_b32_e64 v185, v185, -v185, vcc
	v_fmac_f32_e32 v185, v184, v186
	v_mov_b32_e32 v184, v185
.LBB0_943:
	s_or_b64 exec, exec, s[28:29]
	s_waitcnt lgkmcnt(0)
	v_add_u32_e32 v185, 0x12c00, v138
	v_cvt_pk_bf16_f32 v184, v184, s0
	v_or_b32_e32 v187, 51, v134
	global_store_short v185, v184, s[66:67]
	v_or_b32_e32 v184, v136, v187
	v_ashrrev_i32_e32 v185, 31, v184
	v_lshl_add_u64 v[184:185], v[184:185], 2, s[36:37]
	v_mov_b32_e32 v184, v219
	s_nop 0
	v_mul_f32_e32 v185, v45, v184
	s_nop 1
	v_mov_b32_dpp v186, v185 row_ror:8 row_mask:0xf bank_mask:0xf
	v_cndmask_b32_e64 v45, v187, v135, s[38:39]
	s_and_saveexec_b64 s[28:29], s[20:21]
	s_cbranch_execz .LBB0_945
	v_lshl_or_b32 v187, v45, 6, v50
	global_load_dwordx2 v[188:189], v187, s[76:77]
	s_waitcnt vmcnt(0) lgkmcnt(0)
	v_mul_f32_e32 v186, v189, v186
	v_cndmask_b32_e64 v186, v186, -v186, vcc
	v_fmac_f32_e32 v186, v185, v188
	v_mov_b32_e32 v185, v186
.LBB0_945:
	s_or_b64 exec, exec, s[28:29]
	s_waitcnt lgkmcnt(0)
	v_add_u32_e32 v186, 0x13200, v138
	v_cvt_pk_bf16_f32 v185, v185, s0
	v_or_b32_e32 v188, 56, v134
	global_store_short v186, v185, s[66:67]
	v_or_b32_e32 v186, v136, v188
	v_ashrrev_i32_e32 v187, 31, v186
	v_lshl_add_u64 v[186:187], v[186:187], 2, s[36:37]
	v_mov_b32_e32 v185, v220
	s_nop 0
	v_mul_f32_e32 v186, v46, v185
	s_nop 1
	v_mov_b32_dpp v187, v186 row_ror:8 row_mask:0xf bank_mask:0xf
	v_cndmask_b32_e64 v46, v188, v135, s[38:39]
	s_and_saveexec_b64 s[28:29], s[20:21]
	s_cbranch_execz .LBB0_947
	v_lshl_or_b32 v188, v46, 6, v50
	global_load_dwordx2 v[188:189], v188, s[76:77]
	s_waitcnt vmcnt(0) lgkmcnt(0)
	v_mul_f32_e32 v187, v189, v187
	v_cndmask_b32_e64 v187, v187, -v187, vcc
	v_fmac_f32_e32 v187, v186, v188
	v_mov_b32_e32 v186, v187
.LBB0_947:
	s_or_b64 exec, exec, s[28:29]
	s_waitcnt lgkmcnt(0)
	v_add_u32_e32 v187, 0x15000, v138
	v_cvt_pk_bf16_f32 v186, v186, s0
	v_or_b32_e32 v189, 57, v134
	global_store_short v187, v186, s[66:67]
	v_or_b32_e32 v186, v136, v189
	v_ashrrev_i32_e32 v187, 31, v186
	v_lshl_add_u64 v[186:187], v[186:187], 2, s[36:37]
	v_mov_b32_e32 v186, v221
	s_nop 0
	v_mul_f32_e32 v187, v47, v186
	s_nop 1
	v_mov_b32_dpp v188, v187 row_ror:8 row_mask:0xf bank_mask:0xf
	v_cndmask_b32_e64 v47, v189, v135, s[38:39]
	s_and_saveexec_b64 s[28:29], s[20:21]
	s_cbranch_execz .LBB0_949
	v_lshl_or_b32 v189, v47, 6, v50
	global_load_dwordx2 v[190:191], v189, s[76:77]
	s_waitcnt vmcnt(0) lgkmcnt(0)
	v_mul_f32_e32 v188, v191, v188
	v_cndmask_b32_e64 v188, v188, -v188, vcc
	v_fmac_f32_e32 v188, v187, v190
	v_mov_b32_e32 v187, v188
.LBB0_949:
	s_or_b64 exec, exec, s[28:29]
	s_waitcnt lgkmcnt(0)
	v_add_u32_e32 v188, 0x15600, v138
	v_cvt_pk_bf16_f32 v187, v187, s0
	v_or_b32_e32 v190, 58, v134
	global_store_short v188, v187, s[66:67]
	v_or_b32_e32 v188, v136, v190
	v_ashrrev_i32_e32 v189, 31, v188
	v_lshl_add_u64 v[188:189], v[188:189], 2, s[36:37]
	v_mov_b32_e32 v187, v222
	s_nop 0
	v_mul_f32_e32 v188, v48, v187
	s_nop 1
	v_mov_b32_dpp v189, v188 row_ror:8 row_mask:0xf bank_mask:0xf
	v_cndmask_b32_e64 v48, v190, v135, s[38:39]
	s_and_saveexec_b64 s[28:29], s[20:21]
	s_cbranch_execz .LBB0_951
	v_lshl_or_b32 v190, v48, 6, v50
	global_load_dwordx2 v[190:191], v190, s[76:77]
	s_waitcnt vmcnt(0) lgkmcnt(0)
	v_mul_f32_e32 v189, v191, v189
	v_cndmask_b32_e64 v189, v189, -v189, vcc
	v_fmac_f32_e32 v189, v188, v190
	v_mov_b32_e32 v188, v189
.LBB0_951:
	s_or_b64 exec, exec, s[28:29]
	s_waitcnt lgkmcnt(0)
	v_add_u32_e32 v189, 0x15c00, v138
	v_cvt_pk_bf16_f32 v188, v188, s0
	v_or_b32_e32 v190, 59, v134
	global_store_short v189, v188, s[66:67]
	v_or_b32_e32 v188, v136, v190
	v_ashrrev_i32_e32 v189, 31, v188
	v_lshl_add_u64 v[188:189], v[188:189], 2, s[36:37]
	v_mov_b32_e32 v134, v223
	s_nop 0
	v_mul_f32_e32 v136, v49, v134
	s_nop 1
	v_mov_b32_dpp v188, v136 row_ror:8 row_mask:0xf bank_mask:0xf
	v_cndmask_b32_e64 v49, v190, v135, s[38:39]
	s_and_saveexec_b64 s[28:29], s[20:21]
	s_cbranch_execz .LBB0_953
	v_lshl_or_b32 v135, v49, 6, v50
	global_load_dwordx2 v[190:191], v135, s[76:77]
	s_waitcnt vmcnt(0) lgkmcnt(0)
	v_mul_f32_e32 v135, v191, v188
	v_cndmask_b32_e64 v135, v135, -v135, vcc
	v_fmac_f32_e32 v135, v136, v190
	v_mov_b32_e32 v136, v135
.LBB0_953:
	s_or_b64 exec, exec, s[28:29]
	v_add_u32_e32 v135, 0x16200, v138
	v_cvt_pk_bf16_f32 v136, v136, s0
	v_or_b32_e32 v132, 32, v132
	global_store_short v135, v136, s[66:67]
	v_ashrrev_i32_e32 v135, 5, v132
	s_mov_b32 s20, 0x55555556
	v_mul_hi_i32 v136, v135, s20
	v_lshrrev_b32_e32 v138, 31, v136
	v_mul_f32_e32 v131, v16, v131
	v_add_u32_e32 v136, v136, v138
	s_nop 1
	v_mov_b32_dpp v16, v131 row_ror:8 row_mask:0xf bank_mask:0xf
	v_lshl_add_u32 v136, v136, 1, v136
	v_sub_u32_e32 v135, v135, v136
	v_cmp_eq_u32_e64 s[38:39], 2, v135
	s_and_b64 s[0:1], s[0:1], s[38:39]
	s_and_saveexec_b64 s[20:21], s[0:1]
	s_cbranch_execz .LBB0_955
	v_lshl_or_b32 v133, v133, 6, v50
	s_waitcnt lgkmcnt(1)
	global_load_dwordx2 v[188:189], v133, s[76:77]
	s_waitcnt vmcnt(0) lgkmcnt(0)
	v_mul_f32_e32 v16, v189, v16
	v_cndmask_b32_e64 v16, v16, -v16, vcc
	v_fmac_f32_e32 v16, v131, v188
	v_mov_b32_e32 v131, v16
.LBB0_955:
	s_or_b64 exec, exec, s[20:21]
	v_mul_f32_e32 v17, v17, v137
	s_nop 1
	v_mov_b32_dpp v133, v17 row_ror:8 row_mask:0xf bank_mask:0xf
	s_waitcnt lgkmcnt(1)
	v_add_lshl_u32 v16, v130, v132, 1
	v_cvt_pk_bf16_f32 v130, v131, s0
	global_store_short v16, v130, s[66:67]
	s_and_saveexec_b64 s[20:21], s[0:1]
	s_cbranch_execz .LBB0_957
	v_lshl_or_b32 v51, v51, 6, v50
	global_load_dwordx2 v[130:131], v51, s[76:77]
	s_waitcnt vmcnt(0) lgkmcnt(0)
	v_mul_f32_e32 v51, v131, v133
	v_cndmask_b32_e64 v51, v51, -v51, vcc
	v_fmac_f32_e32 v51, v17, v130
	v_mov_b32_e32 v17, v51
.LBB0_957:
	s_or_b64 exec, exec, s[20:21]
	v_mul_f32_e32 v18, v18, v139
	s_nop 1
	v_mov_b32_dpp v51, v18 row_ror:8 row_mask:0xf bank_mask:0xf
	v_add_u32_e32 v130, 0x600, v16
	v_cvt_pk_bf16_f32 v17, v17, s0
	global_store_short v130, v17, s[66:67]
	s_and_saveexec_b64 s[20:21], s[0:1]
	s_cbranch_execz .LBB0_959
	v_lshl_or_b32 v17, v52, 6, v50
	global_load_dwordx2 v[130:131], v17, s[76:77]
	s_waitcnt vmcnt(0) lgkmcnt(0)
	v_mul_f32_e32 v17, v131, v51
	v_cndmask_b32_e64 v17, v17, -v17, vcc
	v_fmac_f32_e32 v17, v18, v130
	v_mov_b32_e32 v18, v17
.LBB0_959:
	s_or_b64 exec, exec, s[20:21]
	v_mul_f32_e32 v17, v19, v140
	s_nop 1
	v_mov_b32_dpp v19, v17 row_ror:8 row_mask:0xf bank_mask:0xf
	s_waitcnt lgkmcnt(1)
	v_add_u32_e32 v51, 0xc00, v16
	v_cvt_pk_bf16_f32 v18, v18, s0
	global_store_short v51, v18, s[66:67]
	s_and_saveexec_b64 s[20:21], s[0:1]
	s_cbranch_execz .LBB0_961
	v_lshl_or_b32 v18, v53, 6, v50
	global_load_dwordx2 v[52:53], v18, s[76:77]
	s_waitcnt vmcnt(0) lgkmcnt(0)
	v_mul_f32_e32 v18, v53, v19
	v_cndmask_b32_e64 v18, v18, -v18, vcc
	v_fmac_f32_e32 v18, v17, v52
	v_mov_b32_e32 v17, v18
.LBB0_961:
	s_or_b64 exec, exec, s[20:21]
	v_mul_f32_e32 v18, v20, v141
	s_waitcnt lgkmcnt(0)
	s_nop 1
	v_mov_b32_dpp v19, v18 row_ror:8 row_mask:0xf bank_mask:0xf
	v_add_u32_e32 v20, 0x1200, v16
	v_cvt_pk_bf16_f32 v17, v17, s0
	global_store_short v20, v17, s[66:67]
	s_and_saveexec_b64 s[20:21], s[0:1]
	s_cbranch_execz .LBB0_963
	v_lshl_or_b32 v17, v54, 6, v50
	global_load_dwordx2 v[52:53], v17, s[76:77]
	s_waitcnt vmcnt(0) lgkmcnt(0)
	v_mul_f32_e32 v17, v53, v19
	v_cndmask_b32_e64 v17, v17, -v17, vcc
	v_fmac_f32_e32 v17, v18, v52
	v_mov_b32_e32 v18, v17
.LBB0_963:
	s_or_b64 exec, exec, s[20:21]
	v_mul_f32_e32 v17, v21, v142
	s_waitcnt lgkmcnt(0)
	s_nop 1
	v_mov_b32_dpp v19, v17 row_ror:8 row_mask:0xf bank_mask:0xf
	v_add_u32_e32 v20, 0x3000, v16
	v_cvt_pk_bf16_f32 v18, v18, s0
	global_store_short v20, v18, s[66:67]
	s_and_saveexec_b64 s[20:21], s[0:1]
	s_cbranch_execz .LBB0_965
	v_lshl_or_b32 v18, v55, 6, v50
	global_load_dwordx2 v[20:21], v18, s[76:77]
	s_waitcnt vmcnt(0) lgkmcnt(0)
	v_mul_f32_e32 v18, v21, v19
	v_cndmask_b32_e64 v18, v18, -v18, vcc
	v_fmac_f32_e32 v18, v17, v20
	v_mov_b32_e32 v17, v18
.LBB0_965:
	s_or_b64 exec, exec, s[20:21]
	v_mul_f32_e32 v18, v22, v143
	s_waitcnt lgkmcnt(0)
	s_nop 1
	v_mov_b32_dpp v19, v18 row_ror:8 row_mask:0xf bank_mask:0xf
	v_add_u32_e32 v20, 0x3600, v16
	v_cvt_pk_bf16_f32 v17, v17, s0
	global_store_short v20, v17, s[66:67]
	s_and_saveexec_b64 s[20:21], s[0:1]
	s_cbranch_execz .LBB0_967
	v_lshl_or_b32 v17, v56, 6, v50
	global_load_dwordx2 v[20:21], v17, s[76:77]
	s_waitcnt vmcnt(0) lgkmcnt(0)
	v_mul_f32_e32 v17, v21, v19
	v_cndmask_b32_e64 v17, v17, -v17, vcc
	v_fmac_f32_e32 v17, v18, v20
	v_mov_b32_e32 v18, v17
.LBB0_967:
	s_or_b64 exec, exec, s[20:21]
	v_mul_f32_e32 v17, v23, v144
	s_waitcnt lgkmcnt(0)
	s_nop 1
	v_mov_b32_dpp v19, v17 row_ror:8 row_mask:0xf bank_mask:0xf
	v_add_u32_e32 v20, 0x3c00, v16
	v_cvt_pk_bf16_f32 v18, v18, s0
	global_store_short v20, v18, s[66:67]
	s_and_saveexec_b64 s[20:21], s[0:1]
	s_cbranch_execz .LBB0_969
	v_lshl_or_b32 v18, v57, 6, v50
	global_load_dwordx2 v[20:21], v18, s[76:77]
	s_waitcnt vmcnt(0) lgkmcnt(0)
	v_mul_f32_e32 v18, v21, v19
	v_cndmask_b32_e64 v18, v18, -v18, vcc
	v_fmac_f32_e32 v18, v17, v20
	v_mov_b32_e32 v17, v18
.LBB0_969:
	s_or_b64 exec, exec, s[20:21]
	v_mul_f32_e32 v18, v24, v145
	s_waitcnt lgkmcnt(0)
	s_nop 1
	v_mov_b32_dpp v19, v18 row_ror:8 row_mask:0xf bank_mask:0xf
	v_add_u32_e32 v20, 0x4200, v16
	v_cvt_pk_bf16_f32 v17, v17, s0
	global_store_short v20, v17, s[66:67]
	s_and_saveexec_b64 s[20:21], s[0:1]
	s_cbranch_execz .LBB0_971
	v_lshl_or_b32 v17, v58, 6, v50
	global_load_dwordx2 v[20:21], v17, s[76:77]
	s_waitcnt vmcnt(0) lgkmcnt(0)
	v_mul_f32_e32 v17, v21, v19
	v_cndmask_b32_e64 v17, v17, -v17, vcc
	v_fmac_f32_e32 v17, v18, v20
	v_mov_b32_e32 v18, v17
.LBB0_971:
	s_or_b64 exec, exec, s[20:21]
	v_mul_f32_e32 v17, v25, v146
	s_waitcnt lgkmcnt(0)
	s_nop 1
	v_mov_b32_dpp v19, v17 row_ror:8 row_mask:0xf bank_mask:0xf
	v_add_u32_e32 v20, 0x6000, v16
	v_cvt_pk_bf16_f32 v18, v18, s0
	global_store_short v20, v18, s[66:67]
	s_and_saveexec_b64 s[20:21], s[0:1]
	s_cbranch_execz .LBB0_973
	v_lshl_or_b32 v18, v59, 6, v50
	global_load_dwordx2 v[20:21], v18, s[76:77]
	s_waitcnt vmcnt(0) lgkmcnt(0)
	v_mul_f32_e32 v18, v21, v19
	v_cndmask_b32_e64 v18, v18, -v18, vcc
	v_fmac_f32_e32 v18, v17, v20
	v_mov_b32_e32 v17, v18
.LBB0_973:
	s_or_b64 exec, exec, s[20:21]
	v_mul_f32_e32 v18, v26, v147
	s_waitcnt lgkmcnt(0)
	s_nop 1
	v_mov_b32_dpp v19, v18 row_ror:8 row_mask:0xf bank_mask:0xf
	v_add_u32_e32 v20, 0x6600, v16
	v_cvt_pk_bf16_f32 v17, v17, s0
	global_store_short v20, v17, s[66:67]
	s_and_saveexec_b64 s[20:21], s[0:1]
	s_cbranch_execz .LBB0_975
	v_lshl_or_b32 v17, v60, 6, v50
	global_load_dwordx2 v[20:21], v17, s[76:77]
	s_waitcnt vmcnt(0) lgkmcnt(0)
	v_mul_f32_e32 v17, v21, v19
	v_cndmask_b32_e64 v17, v17, -v17, vcc
	v_fmac_f32_e32 v17, v18, v20
	v_mov_b32_e32 v18, v17
.LBB0_975:
	s_or_b64 exec, exec, s[20:21]
	v_mul_f32_e32 v17, v27, v148
	s_waitcnt lgkmcnt(0)
	s_nop 1
	v_mov_b32_dpp v19, v17 row_ror:8 row_mask:0xf bank_mask:0xf
	v_add_u32_e32 v20, 0x6c00, v16
	v_cvt_pk_bf16_f32 v18, v18, s0
	global_store_short v20, v18, s[66:67]
	s_and_saveexec_b64 s[20:21], s[0:1]
	s_cbranch_execz .LBB0_977
	v_lshl_or_b32 v18, v61, 6, v50
	global_load_dwordx2 v[20:21], v18, s[76:77]
	s_waitcnt vmcnt(0) lgkmcnt(0)
	v_mul_f32_e32 v18, v21, v19
	v_cndmask_b32_e64 v18, v18, -v18, vcc
	v_fmac_f32_e32 v18, v17, v20
	v_mov_b32_e32 v17, v18
.LBB0_977:
	s_or_b64 exec, exec, s[20:21]
	v_mul_f32_e32 v18, v28, v149
	s_waitcnt lgkmcnt(0)
	s_nop 1
	v_mov_b32_dpp v19, v18 row_ror:8 row_mask:0xf bank_mask:0xf
	v_add_u32_e32 v20, 0x7200, v16
	v_cvt_pk_bf16_f32 v17, v17, s0
	global_store_short v20, v17, s[66:67]
	s_and_saveexec_b64 s[20:21], s[0:1]
	s_cbranch_execz .LBB0_979
	v_lshl_or_b32 v17, v62, 6, v50
	global_load_dwordx2 v[20:21], v17, s[76:77]
	s_waitcnt vmcnt(0) lgkmcnt(0)
	v_mul_f32_e32 v17, v21, v19
	v_cndmask_b32_e64 v17, v17, -v17, vcc
	v_fmac_f32_e32 v17, v18, v20
	v_mov_b32_e32 v18, v17
.LBB0_979:
	s_or_b64 exec, exec, s[20:21]
	v_mul_f32_e32 v17, v29, v150
	s_waitcnt lgkmcnt(0)
	s_nop 1
	v_mov_b32_dpp v19, v17 row_ror:8 row_mask:0xf bank_mask:0xf
	v_add_u32_e32 v20, 0x9000, v16
	v_cvt_pk_bf16_f32 v18, v18, s0
	global_store_short v20, v18, s[66:67]
	s_and_saveexec_b64 s[20:21], s[0:1]
	s_cbranch_execz .LBB0_981
	v_lshl_or_b32 v18, v63, 6, v50
	global_load_dwordx2 v[20:21], v18, s[76:77]
	s_waitcnt vmcnt(0) lgkmcnt(0)
	v_mul_f32_e32 v18, v21, v19
	v_cndmask_b32_e64 v18, v18, -v18, vcc
	v_fmac_f32_e32 v18, v17, v20
	v_mov_b32_e32 v17, v18
.LBB0_981:
	s_or_b64 exec, exec, s[20:21]
	v_mul_f32_e32 v18, v30, v151
	s_waitcnt lgkmcnt(0)
	s_nop 1
	v_mov_b32_dpp v19, v18 row_ror:8 row_mask:0xf bank_mask:0xf
	v_add_u32_e32 v20, 0x9600, v16
	v_cvt_pk_bf16_f32 v17, v17, s0
	global_store_short v20, v17, s[66:67]
	s_and_saveexec_b64 s[20:21], s[0:1]
	s_cbranch_execz .LBB0_983
	v_lshl_or_b32 v17, v64, 6, v50
	global_load_dwordx2 v[20:21], v17, s[76:77]
	s_waitcnt vmcnt(0) lgkmcnt(0)
	v_mul_f32_e32 v17, v21, v19
	v_cndmask_b32_e64 v17, v17, -v17, vcc
	v_fmac_f32_e32 v17, v18, v20
	v_mov_b32_e32 v18, v17
.LBB0_983:
	s_or_b64 exec, exec, s[20:21]
	v_mul_f32_e32 v17, v31, v152
	s_waitcnt lgkmcnt(0)
	s_nop 1
	v_mov_b32_dpp v19, v17 row_ror:8 row_mask:0xf bank_mask:0xf
	v_add_u32_e32 v20, 0x9c00, v16
	v_cvt_pk_bf16_f32 v18, v18, s0
	global_store_short v20, v18, s[66:67]
	s_and_saveexec_b64 s[20:21], s[0:1]
	s_cbranch_execz .LBB0_985
	v_lshl_or_b32 v18, v65, 6, v50
	global_load_dwordx2 v[20:21], v18, s[76:77]
	s_waitcnt vmcnt(0) lgkmcnt(0)
	v_mul_f32_e32 v18, v21, v19
	v_cndmask_b32_e64 v18, v18, -v18, vcc
	v_fmac_f32_e32 v18, v17, v20
	v_mov_b32_e32 v17, v18
.LBB0_985:
	s_or_b64 exec, exec, s[20:21]
	v_mul_f32_e32 v0, v0, v153
	s_nop 1
	v_mov_b32_dpp v18, v0 row_ror:8 row_mask:0xf bank_mask:0xf
	s_waitcnt lgkmcnt(1)
	v_add_u32_e32 v19, 0xa200, v16
	v_cvt_pk_bf16_f32 v17, v17, s0
	global_store_short v19, v17, s[66:67]
	s_and_saveexec_b64 s[20:21], s[0:1]
	s_cbranch_execz .LBB0_987
	v_lshl_or_b32 v17, v34, 6, v50
	global_load_dwordx2 v[20:21], v17, s[76:77]
	s_waitcnt vmcnt(0) lgkmcnt(0)
	v_mul_f32_e32 v17, v21, v18
	v_cndmask_b32_e64 v17, v17, -v17, vcc
	v_fmac_f32_e32 v17, v0, v20
	v_mov_b32_e32 v0, v17
.LBB0_987:
	s_or_b64 exec, exec, s[20:21]
	v_mul_f32_e32 v1, v1, v154
	s_nop 1
	v_mov_b32_dpp v17, v1 row_ror:8 row_mask:0xf bank_mask:0xf
	s_waitcnt lgkmcnt(1)
	v_add_u32_e32 v18, 0xc000, v16
	v_cvt_pk_bf16_f32 v0, v0, s0
	global_store_short v18, v0, s[66:67]
	s_and_saveexec_b64 s[20:21], s[0:1]
	s_cbranch_execz .LBB0_989
	v_lshl_or_b32 v0, v35, 6, v50
	global_load_dwordx2 v[18:19], v0, s[76:77]
	s_waitcnt vmcnt(0) lgkmcnt(0)
	v_mul_f32_e32 v0, v19, v17
	v_cndmask_b32_e64 v0, v0, -v0, vcc
	v_fmac_f32_e32 v0, v1, v18
	v_mov_b32_e32 v1, v0
.LBB0_989:
	s_or_b64 exec, exec, s[20:21]
	v_mul_f32_e32 v0, v2, v155
	s_nop 1
	v_mov_b32_dpp v2, v0 row_ror:8 row_mask:0xf bank_mask:0xf
	s_waitcnt lgkmcnt(1)
	v_add_u32_e32 v17, 0xc600, v16
	v_cvt_pk_bf16_f32 v1, v1, s0
	global_store_short v17, v1, s[66:67]
	s_and_saveexec_b64 s[20:21], s[0:1]
	s_cbranch_execz .LBB0_991
	v_lshl_or_b32 v1, v36, 6, v50
	global_load_dwordx2 v[18:19], v1, s[76:77]
	s_waitcnt vmcnt(0) lgkmcnt(0)
	v_mul_f32_e32 v1, v19, v2
	v_cndmask_b32_e64 v1, v1, -v1, vcc
	v_fmac_f32_e32 v1, v0, v18
	v_mov_b32_e32 v0, v1
.LBB0_991:
	s_or_b64 exec, exec, s[20:21]
	v_mul_f32_e32 v1, v3, v156
	s_waitcnt lgkmcnt(0)
	s_nop 1
	v_mov_b32_dpp v2, v1 row_ror:8 row_mask:0xf bank_mask:0xf
	v_add_u32_e32 v3, 0xcc00, v16
	v_cvt_pk_bf16_f32 v0, v0, s0
	global_store_short v3, v0, s[66:67]
	s_and_saveexec_b64 s[20:21], s[0:1]
	s_cbranch_execz .LBB0_993
	v_lshl_or_b32 v0, v37, 6, v50
	global_load_dwordx2 v[18:19], v0, s[76:77]
	s_waitcnt vmcnt(0) lgkmcnt(0)
	v_mul_f32_e32 v0, v19, v2
	v_cndmask_b32_e64 v0, v0, -v0, vcc
	v_fmac_f32_e32 v0, v1, v18
	v_mov_b32_e32 v1, v0
.LBB0_993:
	s_or_b64 exec, exec, s[20:21]
	v_mul_f32_e32 v0, v4, v157
	s_waitcnt lgkmcnt(0)
	s_nop 1
	v_mov_b32_dpp v2, v0 row_ror:8 row_mask:0xf bank_mask:0xf
	v_add_u32_e32 v3, 0xd200, v16
	v_cvt_pk_bf16_f32 v1, v1, s0
	global_store_short v3, v1, s[66:67]
	s_and_saveexec_b64 s[20:21], s[0:1]
	s_cbranch_execz .LBB0_995
	v_lshl_or_b32 v1, v38, 6, v50
	global_load_dwordx2 v[18:19], v1, s[76:77]
	s_waitcnt vmcnt(0) lgkmcnt(0)
	v_mul_f32_e32 v1, v19, v2
	v_cndmask_b32_e64 v1, v1, -v1, vcc
	v_fmac_f32_e32 v1, v0, v18
	v_mov_b32_e32 v0, v1
.LBB0_995:
	s_or_b64 exec, exec, s[20:21]
	v_mul_f32_e32 v1, v5, v160
	s_waitcnt lgkmcnt(0)
	s_nop 1
	v_mov_b32_dpp v2, v1 row_ror:8 row_mask:0xf bank_mask:0xf
	v_add_u32_e32 v3, 0xf000, v16
	v_cvt_pk_bf16_f32 v0, v0, s0
	global_store_short v3, v0, s[66:67]
	s_and_saveexec_b64 s[20:21], s[0:1]
	s_cbranch_execz .LBB0_997
	v_lshl_or_b32 v0, v39, 6, v50
	global_load_dwordx2 v[4:5], v0, s[76:77]
	s_waitcnt vmcnt(0) lgkmcnt(0)
	v_mul_f32_e32 v0, v5, v2
	v_cndmask_b32_e64 v0, v0, -v0, vcc
	v_fmac_f32_e32 v0, v1, v4
	v_mov_b32_e32 v1, v0
.LBB0_997:
	s_or_b64 exec, exec, s[20:21]
	v_mul_f32_e32 v0, v6, v161
	s_waitcnt lgkmcnt(0)
	s_nop 1
	v_mov_b32_dpp v2, v0 row_ror:8 row_mask:0xf bank_mask:0xf
	v_add_u32_e32 v3, 0xf600, v16
	v_cvt_pk_bf16_f32 v1, v1, s0
	global_store_short v3, v1, s[66:67]
	s_and_saveexec_b64 s[20:21], s[0:1]
	s_cbranch_execz .LBB0_999
	v_lshl_or_b32 v1, v40, 6, v50
	global_load_dwordx2 v[4:5], v1, s[76:77]
	s_waitcnt vmcnt(0) lgkmcnt(0)
	v_mul_f32_e32 v1, v5, v2
	v_cndmask_b32_e64 v1, v1, -v1, vcc
	v_fmac_f32_e32 v1, v0, v4
	v_mov_b32_e32 v0, v1
.LBB0_999:
	s_or_b64 exec, exec, s[20:21]
	v_mul_f32_e32 v1, v7, v180
	s_waitcnt lgkmcnt(0)
	s_nop 1
	v_mov_b32_dpp v2, v1 row_ror:8 row_mask:0xf bank_mask:0xf
	v_add_u32_e32 v3, 0xfc00, v16
	v_cvt_pk_bf16_f32 v0, v0, s0
	global_store_short v3, v0, s[66:67]
	s_and_saveexec_b64 s[20:21], s[0:1]
	s_cbranch_execz .LBB0_1001
	v_lshl_or_b32 v0, v41, 6, v50
	global_load_dwordx2 v[4:5], v0, s[76:77]
	s_waitcnt vmcnt(0) lgkmcnt(0)
	v_mul_f32_e32 v0, v5, v2
	v_cndmask_b32_e64 v0, v0, -v0, vcc
	v_fmac_f32_e32 v0, v1, v4
	v_mov_b32_e32 v1, v0
.LBB0_1001:
	s_or_b64 exec, exec, s[20:21]
	v_mul_f32_e32 v0, v8, v181
	s_waitcnt lgkmcnt(0)
	s_nop 1
	v_mov_b32_dpp v2, v0 row_ror:8 row_mask:0xf bank_mask:0xf
	v_add_u32_e32 v3, 0x10200, v16
	v_cvt_pk_bf16_f32 v1, v1, s0
	global_store_short v3, v1, s[66:67]
	s_and_saveexec_b64 s[20:21], s[0:1]
	s_cbranch_execz .LBB0_1003
	v_lshl_or_b32 v1, v42, 6, v50
	global_load_dwordx2 v[4:5], v1, s[76:77]
	s_waitcnt vmcnt(0) lgkmcnt(0)
	v_mul_f32_e32 v1, v5, v2
	v_cndmask_b32_e64 v1, v1, -v1, vcc
	v_fmac_f32_e32 v1, v0, v4
	v_mov_b32_e32 v0, v1
.LBB0_1003:
	s_or_b64 exec, exec, s[20:21]
	v_mul_f32_e32 v1, v9, v182
	s_waitcnt lgkmcnt(0)
	s_nop 1
	v_mov_b32_dpp v2, v1 row_ror:8 row_mask:0xf bank_mask:0xf
	v_add_u32_e32 v3, 0x12000, v16
	v_cvt_pk_bf16_f32 v0, v0, s0
	global_store_short v3, v0, s[66:67]
	s_and_saveexec_b64 s[20:21], s[0:1]
	s_cbranch_execz .LBB0_1005
	v_lshl_or_b32 v0, v43, 6, v50
	global_load_dwordx2 v[4:5], v0, s[76:77]
	s_waitcnt vmcnt(0) lgkmcnt(0)
	v_mul_f32_e32 v0, v5, v2
	v_cndmask_b32_e64 v0, v0, -v0, vcc
	v_fmac_f32_e32 v0, v1, v4
	v_mov_b32_e32 v1, v0
.LBB0_1005:
	s_or_b64 exec, exec, s[20:21]
	v_mul_f32_e32 v0, v10, v183
	s_waitcnt lgkmcnt(0)
	s_nop 1
	v_mov_b32_dpp v2, v0 row_ror:8 row_mask:0xf bank_mask:0xf
	v_add_u32_e32 v3, 0x12600, v16
	v_cvt_pk_bf16_f32 v1, v1, s0
	global_store_short v3, v1, s[66:67]
	s_and_saveexec_b64 s[20:21], s[0:1]
	s_cbranch_execz .LBB0_1007
	v_lshl_or_b32 v1, v44, 6, v50
	global_load_dwordx2 v[4:5], v1, s[76:77]
	s_waitcnt vmcnt(0) lgkmcnt(0)
	v_mul_f32_e32 v1, v5, v2
	v_cndmask_b32_e64 v1, v1, -v1, vcc
	v_fmac_f32_e32 v1, v0, v4
	v_mov_b32_e32 v0, v1
.LBB0_1007:
	s_or_b64 exec, exec, s[20:21]
	v_mul_f32_e32 v1, v11, v184
	s_waitcnt lgkmcnt(0)
	s_nop 1
	v_mov_b32_dpp v2, v1 row_ror:8 row_mask:0xf bank_mask:0xf
	v_add_u32_e32 v3, 0x12c00, v16
	v_cvt_pk_bf16_f32 v0, v0, s0
	global_store_short v3, v0, s[66:67]
	s_and_saveexec_b64 s[20:21], s[0:1]
	s_cbranch_execz .LBB0_1009
	v_lshl_or_b32 v0, v45, 6, v50
	global_load_dwordx2 v[4:5], v0, s[76:77]
	s_waitcnt vmcnt(0) lgkmcnt(0)
	v_mul_f32_e32 v0, v5, v2
	v_cndmask_b32_e64 v0, v0, -v0, vcc
	v_fmac_f32_e32 v0, v1, v4
	v_mov_b32_e32 v1, v0
.LBB0_1009:
	s_or_b64 exec, exec, s[20:21]
	v_mul_f32_e32 v0, v12, v185
	s_waitcnt lgkmcnt(0)
	s_nop 1
	v_mov_b32_dpp v2, v0 row_ror:8 row_mask:0xf bank_mask:0xf
	v_add_u32_e32 v3, 0x13200, v16
	v_cvt_pk_bf16_f32 v1, v1, s0
	global_store_short v3, v1, s[66:67]
	s_and_saveexec_b64 s[20:21], s[0:1]
	s_cbranch_execz .LBB0_1011
	v_lshl_or_b32 v1, v46, 6, v50
	global_load_dwordx2 v[4:5], v1, s[76:77]
	s_waitcnt vmcnt(0) lgkmcnt(0)
	v_mul_f32_e32 v1, v5, v2
	v_cndmask_b32_e64 v1, v1, -v1, vcc
	v_fmac_f32_e32 v1, v0, v4
	v_mov_b32_e32 v0, v1
.LBB0_1011:
	s_or_b64 exec, exec, s[20:21]
	v_mul_f32_e32 v1, v13, v186
	s_waitcnt lgkmcnt(0)
	s_nop 1
	v_mov_b32_dpp v2, v1 row_ror:8 row_mask:0xf bank_mask:0xf
	v_add_u32_e32 v3, 0x15000, v16
	v_cvt_pk_bf16_f32 v0, v0, s0
	global_store_short v3, v0, s[66:67]
	s_and_saveexec_b64 s[20:21], s[0:1]
	s_cbranch_execz .LBB0_1013
	v_lshl_or_b32 v0, v47, 6, v50
	global_load_dwordx2 v[4:5], v0, s[76:77]
	s_waitcnt vmcnt(0) lgkmcnt(0)
	v_mul_f32_e32 v0, v5, v2
	v_cndmask_b32_e64 v0, v0, -v0, vcc
	v_fmac_f32_e32 v0, v1, v4
	v_mov_b32_e32 v1, v0
.LBB0_1013:
	s_or_b64 exec, exec, s[20:21]
	v_mul_f32_e32 v0, v14, v187
	s_waitcnt lgkmcnt(0)
	s_nop 1
	v_mov_b32_dpp v2, v0 row_ror:8 row_mask:0xf bank_mask:0xf
	v_add_u32_e32 v3, 0x15600, v16
	v_cvt_pk_bf16_f32 v1, v1, s0
	global_store_short v3, v1, s[66:67]
	s_and_saveexec_b64 s[20:21], s[0:1]
	s_cbranch_execz .LBB0_1015
	v_lshl_or_b32 v1, v48, 6, v50
	global_load_dwordx2 v[4:5], v1, s[76:77]
	s_waitcnt vmcnt(0) lgkmcnt(0)
	v_mul_f32_e32 v1, v5, v2
	v_cndmask_b32_e64 v1, v1, -v1, vcc
	v_fmac_f32_e32 v1, v0, v4
	v_mov_b32_e32 v0, v1
.LBB0_1015:
	s_or_b64 exec, exec, s[20:21]
	v_mul_f32_e32 v1, v15, v134
	s_waitcnt lgkmcnt(0)
	s_nop 1
	v_mov_b32_dpp v2, v1 row_ror:8 row_mask:0xf bank_mask:0xf
	v_add_u32_e32 v3, 0x15c00, v16
	v_cvt_pk_bf16_f32 v0, v0, s0
	global_store_short v3, v0, s[66:67]
	s_and_saveexec_b64 s[20:21], s[0:1]
	s_cbranch_execz .LBB0_798
	v_lshl_or_b32 v0, v49, 6, v50
	global_load_dwordx2 v[4:5], v0, s[76:77]
	s_waitcnt vmcnt(0) lgkmcnt(0)
	v_mul_f32_e32 v0, v5, v2
	v_cndmask_b32_e64 v0, v0, -v0, vcc
	v_fmac_f32_e32 v0, v1, v4
	v_mov_b32_e32 v1, v0
	s_branch .LBB0_798
